# combo37: combo23 + pass C output copy de-serialised (eight LDS reads issued together into separate registers, counted lgkmcnt waits before each store)
# baseline (speedup 1.0000x reference)
; #define LAS __attribute__((address_space(3)))
; __device__ __forceinline__ int crow(int r, int hi) { return (r & 3) + 8 * (r >> 2) + 4 * hi; }
; __device__ __forceinline__ float bf2f(unsigned short v) { return __uint_as_float((unsigned)v << 16); }
; __device__ __forceinline__ unsigned f2bf(float f) { return pk2(f, 0.f) & 0xffffu; }
; __device__ __forceinline__ int crow(int r, int hi) { return (r & 3) + 8 * (r >> 2) + 4 * hi; }
; __device__ __forceinline__ void gla_pass_c(LAS unsigned char* ldsl, const bf16_t* __restrict__ proj, const float* __restrict__ Btab, const float* __restrict__ Gst, const float* __restrict__ gout, bf16_t* __restrict__ mixed) {
;     ...
;         { const bf16_t* gp = proj + (row0 + 32 * tb + crw) * NIN + 1024 + h * 128 + ccl * 8; u32x4 sv[8];
; #pragma unroll
;           for (int i = 0; i < 8; ++i) sv[i] = *(const u32x4*)(gp + (size_t)(4 * i) * NIN);
; #pragma unroll
;           for (int i = 0; i < 8; ++i) *(LAS u32x4*)(Lw + (4 * i + crw) * 256 + ccl * 16) = sv[i]; }
;         float gn[4];
; #pragma unroll
;         for (int dvb = 0; dvb < 4; ++dvb) gn[dvb] = gout[32 * dvb + r];
; #pragma unroll
;         for (int i = 0; i < 16; ++i) { const int tr = crow(i, hh);
;             const float tot = half_sum32((o[0][i] * o[0][i] + o[1][i] * o[1][i]) + (o[2][i] * o[2][i] + o[3][i] * o[3][i]));
;             const float rr = __builtin_amdgcn_rsqf(tot * (1.0f / 128.0f) + EPS);
; #pragma unroll
;             for (int dvb = 0; dvb < 4; ++dvb) { const float g = bf2f(Lh[tr * 128 + 32 * dvb + r]);
;                 const float val = o[dvb][i] * rr * gn[dvb] * (g * __builtin_amdgcn_rcpf(1.0f + __expf(-g)));
;                 Lh[(32 + tr) * 128 + 32 * dvb + r] = (bf16_t)f2bf(val); } }
.LBB0_873:
	v_or3_b32 v122, s2, v110, v122
	v_lshlrev_b64 v[64:65], 12, v[122:123]
	v_lshl_add_u64 v[64:65], s[60:61], 0, v[64:65]
	v_lshlrev_b32_e32 v160, 1, v124
	v_lshl_add_u64 v[64:65], v[64:65], 0, v[160:161]
	v_mov_b32_e32 v121, v161
	v_lshl_add_u64 v[92:93], v[64:65], 0, v[120:121]
	v_add_co_u32_e32 v68, vcc, 0x4000, v92
	global_load_dwordx4 v[64:67], v[92:93], off offset:2048
	s_nop 0
	v_addc_co_u32_e32 v69, vcc, 0, v93, vcc
	v_add_co_u32_e32 v72, vcc, 0x8000, v92
	global_load_dwordx4 v[68:71], v[68:69], off offset:2048
	s_nop 0
	v_addc_co_u32_e32 v73, vcc, 0, v93, vcc
	v_add_co_u32_e32 v76, vcc, 0xc000, v92
	global_load_dwordx4 v[72:75], v[72:73], off offset:2048
	s_nop 0
	v_addc_co_u32_e32 v77, vcc, 0, v93, vcc
	v_add_co_u32_e32 v80, vcc, s51, v92
	s_mov_b32 s33, 0x18000
	s_nop 0
	v_addc_co_u32_e32 v81, vcc, 0, v93, vcc
	v_add_co_u32_e32 v84, vcc, s52, v92
	global_load_dwordx4 v[76:79], v[76:77], off offset:2048
	s_nop 0
	v_addc_co_u32_e32 v85, vcc, 0, v93, vcc
	v_add_co_u32_e32 v88, vcc, s33, v92
	global_load_dwordx4 v[80:83], v[80:81], off offset:2048
	s_nop 0
	v_addc_co_u32_e32 v89, vcc, 0, v93, vcc
	s_mov_b32 s2, 0x1c000
	global_load_dwordx4 v[84:87], v[84:85], off offset:2048
	v_add_co_u32_e32 v92, vcc, s2, v92
	global_load_dwordx4 v[88:91], v[88:89], off offset:2048
	s_nop 0
	v_addc_co_u32_e32 v93, vcc, 0, v93, vcc
	global_load_dwordx4 v[92:95], v[92:93], off offset:2048
	s_movk_i32 s2, 0x2000
	s_mov_b32 s42, 0x8000
	s_waitcnt vmcnt(7)
	ds_write_b128 v140, v[64:67]
	s_waitcnt vmcnt(6)
	ds_write_b128 v140, v[68:71] offset:1024
	s_waitcnt vmcnt(5)
	ds_write_b128 v140, v[72:75] offset:2048
	s_waitcnt vmcnt(4)
	ds_write_b128 v140, v[76:79] offset:3072
	s_waitcnt vmcnt(3)
	ds_write_b128 v140, v[80:83] offset:4096
	s_waitcnt vmcnt(2)
	ds_write_b128 v140, v[84:87] offset:5120
	s_waitcnt vmcnt(1)
	ds_write_b128 v140, v[88:91] offset:6144
	s_waitcnt vmcnt(0)
	ds_write_b128 v140, v[92:95] offset:7168
	v_mul_f32_e32 v64, v16, v16
	v_mul_f32_e32 v65, v32, v32
	v_fmac_f32_e32 v64, v0, v0
	v_fmac_f32_e32 v65, v48, v48
	v_add_f32_e32 v64, v64, v65
	ds_read_u16 v144, v138
	ds_read_u16 v145, v138 offset:64
	ds_read_u16 v146, v138 offset:128
	ds_read_u16 v147, v138 offset:192
	s_nop 1
	v_add_f32_dpp v64, v64, v64 quad_perm:[1,0,3,2] row_mask:0xf bank_mask:0xf
	s_nop 1
	v_add_f32_dpp v64, v64, v64 quad_perm:[2,3,0,1] row_mask:0xf bank_mask:0xf
	s_nop 1
	v_add_f32_dpp v64, v64, v64 row_half_mirror row_mask:0xf bank_mask:0xf
	s_nop 1
	v_add_f32_dpp v64, v64, v64 row_mirror row_mask:0xf bank_mask:0xf
	s_waitcnt lgkmcnt(0)
	ds_bpermute_b32 v65, v137, v64
	s_waitcnt lgkmcnt(0)
	v_add_f32_e32 v64, v64, v65
	v_fmamk_f32 v64, v64, 0x3c000000, v199
	v_rsq_f32_e32 v64, v64
	v_lshlrev_b32_e32 v65, 16, v144
	v_mul_f32_e32 v66, 0xbfb8aa3b, v65
	v_exp_f32_e32 v66, v66
	v_mul_f32_e32 v0, v0, v64
	v_mul_f32_e32 v0, v113, v0
	v_mul_f32_e32 v16, v16, v64
	v_add_f32_e32 v66, 1.0, v66
	v_rcp_f32_e32 v66, v66
	v_mul_f32_e32 v16, v130, v16
	v_mul_f32_e32 v65, v66, v65
	v_mul_f32_e32 v0, v0, v65
	v_cvt_pk_bf16_f32 v0, v0, s0
	ds_write_b16 v138, v0 offset:8192
	v_lshlrev_b32_e32 v0, 16, v145
	v_mul_f32_e32 v65, 0xbfb8aa3b, v0
	v_exp_f32_e32 v65, v65
	s_nop 0
	v_add_f32_e32 v65, 1.0, v65
	v_rcp_f32_e32 v65, v65
	s_nop 0
	v_mul_f32_e32 v0, v65, v0
	v_mul_f32_e32 v0, v16, v0
	v_cvt_pk_bf16_f32 v0, v0, s0
	ds_write_b16 v138, v0 offset:8256
	v_mul_f32_e32 v16, v48, v64
	v_mul_f32_e32 v16, v131, v16
	v_lshlrev_b32_e32 v0, 16, v146
	v_mul_f32_e32 v48, 0xbfb8aa3b, v0
	v_exp_f32_e32 v48, v48
	s_nop 0
	v_add_f32_e32 v48, 1.0, v48
	v_rcp_f32_e32 v48, v48
	s_nop 0
	v_mul_f32_e32 v0, v48, v0
	v_mul_f32_e32 v0, v16, v0
	v_cvt_pk_bf16_f32 v0, v0, s0
	ds_write_b16 v138, v0 offset:8320
	v_mul_f32_e32 v16, v32, v64
	v_mul_f32_e32 v16, v132, v16
	v_lshlrev_b32_e32 v0, 16, v147
	v_mul_f32_e32 v32, 0xbfb8aa3b, v0
	v_exp_f32_e32 v32, v32
	s_nop 0
	v_add_f32_e32 v32, 1.0, v32
	v_rcp_f32_e32 v32, v32
	s_nop 0
	v_mul_f32_e32 v0, v32, v0
	v_mul_f32_e32 v0, v16, v0
	v_cvt_pk_bf16_f32 v0, v0, s0
	ds_write_b16 v138, v0 offset:8384
	v_mul_f32_e32 v0, v17, v17
	v_mul_f32_e32 v16, v33, v33
	v_fmac_f32_e32 v0, v1, v1
	v_fmac_f32_e32 v16, v49, v49
	v_add_f32_e32 v0, v0, v16
	ds_read_u16 v144, v138 offset:256
	ds_read_u16 v145, v138 offset:320
	ds_read_u16 v146, v138 offset:384
	ds_read_u16 v147, v138 offset:448
	s_nop 1
	v_add_f32_dpp v0, v0, v0 quad_perm:[1,0,3,2] row_mask:0xf bank_mask:0xf
	s_nop 1
	v_add_f32_dpp v0, v0, v0 quad_perm:[2,3,0,1] row_mask:0xf bank_mask:0xf
	s_nop 1
	v_add_f32_dpp v0, v0, v0 row_half_mirror row_mask:0xf bank_mask:0xf
	s_nop 1
	v_add_f32_dpp v0, v0, v0 row_mirror row_mask:0xf bank_mask:0xf
	s_waitcnt lgkmcnt(0)
	ds_bpermute_b32 v16, v137, v0
	s_waitcnt lgkmcnt(0)
; __device__ __forceinline__ int crow(int r, int hi) { return (r & 3) + 8 * (r >> 2) + 4 * hi; }
; __device__ __forceinline__ float bf2f(unsigned short v) { return __uint_as_float((unsigned)v << 16); }
; __device__ __forceinline__ unsigned f2bf(float f) { return pk2(f, 0.f) & 0xffffu; }
; __device__ __forceinline__ int crow(int r, int hi) { return (r & 3) + 8 * (r >> 2) + 4 * hi; }
; __device__ __forceinline__ void gla_pass_c(LAS unsigned char* ldsl, const bf16_t* __restrict__ proj, const float* __restrict__ Btab, const float* __restrict__ Gst, const float* __restrict__ gout, bf16_t* __restrict__ mixed) {
;     ...
;         for (int i = 0; i < 16; ++i) { const int tr = crow(i, hh);
;             const float tot = half_sum32((o[0][i] * o[0][i] + o[1][i] * o[1][i]) + (o[2][i] * o[2][i] + o[3][i] * o[3][i]));
;             const float rr = __builtin_amdgcn_rsqf(tot * (1.0f / 128.0f) + EPS);
; #pragma unroll
;             for (int dvb = 0; dvb < 4; ++dvb) { const float g = bf2f(Lh[tr * 128 + 32 * dvb + r]);
;                 const float val = o[dvb][i] * rr * gn[dvb] * (g * __builtin_amdgcn_rcpf(1.0f + __expf(-g)));
;                 Lh[(32 + tr) * 128 + 32 * dvb + r] = (bf16_t)f2bf(val); } }
	v_add_f32_e32 v0, v0, v16
	v_fmamk_f32 v0, v0, 0x3c000000, v199
	v_rsq_f32_e32 v0, v0
	v_lshlrev_b32_e32 v16, 16, v144
	v_mul_f32_e32 v32, 0xbfb8aa3b, v16
	v_exp_f32_e32 v32, v32
	v_mul_f32_e32 v1, v1, v0
	v_mul_f32_e32 v1, v113, v1
	v_add_f32_e32 v32, 1.0, v32
	v_rcp_f32_e32 v32, v32
	s_nop 0
	v_mul_f32_e32 v16, v32, v16
	v_mul_f32_e32 v1, v1, v16
	v_cvt_pk_bf16_f32 v1, v1, s0
	ds_write_b16 v138, v1 offset:8448
	v_mul_f32_e32 v16, v17, v0
	v_mul_f32_e32 v16, v130, v16
	v_lshlrev_b32_e32 v1, 16, v145
	v_mul_f32_e32 v17, 0xbfb8aa3b, v1
	v_exp_f32_e32 v17, v17
	s_nop 0
	v_add_f32_e32 v17, 1.0, v17
	v_rcp_f32_e32 v17, v17
	s_nop 0
	v_mul_f32_e32 v1, v17, v1
	v_mul_f32_e32 v1, v16, v1
	v_cvt_pk_bf16_f32 v1, v1, s0
	ds_write_b16 v138, v1 offset:8512
	v_mul_f32_e32 v16, v49, v0
	v_mul_f32_e32 v16, v131, v16
	v_mul_f32_e32 v0, v33, v0
	v_mul_f32_e32 v0, v132, v0
	v_lshlrev_b32_e32 v1, 16, v146
	v_mul_f32_e32 v17, 0xbfb8aa3b, v1
	v_exp_f32_e32 v17, v17
	s_nop 0
	v_add_f32_e32 v17, 1.0, v17
	v_rcp_f32_e32 v17, v17
	s_nop 0
	v_mul_f32_e32 v1, v17, v1
	v_mul_f32_e32 v1, v16, v1
	v_cvt_pk_bf16_f32 v1, v1, s0
	ds_write_b16 v138, v1 offset:8576
	v_lshlrev_b32_e32 v1, 16, v147
	v_mul_f32_e32 v16, 0xbfb8aa3b, v1
	v_exp_f32_e32 v16, v16
	s_nop 0
	v_add_f32_e32 v16, 1.0, v16
	v_rcp_f32_e32 v16, v16
	s_nop 0
	v_mul_f32_e32 v1, v16, v1
	v_mul_f32_e32 v0, v0, v1
	v_cvt_pk_bf16_f32 v0, v0, s0
	ds_write_b16 v138, v0 offset:8640
	v_mul_f32_e32 v0, v18, v18
	v_mul_f32_e32 v1, v34, v34
	v_fmac_f32_e32 v0, v2, v2
	v_fmac_f32_e32 v1, v50, v50
	v_add_f32_e32 v0, v0, v1
	ds_read_u16 v144, v138 offset:512
	ds_read_u16 v145, v138 offset:576
	ds_read_u16 v146, v138 offset:640
	ds_read_u16 v147, v138 offset:704
	s_nop 1
	v_add_f32_dpp v0, v0, v0 quad_perm:[1,0,3,2] row_mask:0xf bank_mask:0xf
	s_nop 1
	v_add_f32_dpp v0, v0, v0 quad_perm:[2,3,0,1] row_mask:0xf bank_mask:0xf
	s_nop 1
	v_add_f32_dpp v0, v0, v0 row_half_mirror row_mask:0xf bank_mask:0xf
	s_nop 1
	v_add_f32_dpp v0, v0, v0 row_mirror row_mask:0xf bank_mask:0xf
	s_waitcnt lgkmcnt(0)
	ds_bpermute_b32 v1, v137, v0
	s_waitcnt lgkmcnt(0)
	v_add_f32_e32 v0, v0, v1
	v_fmamk_f32 v0, v0, 0x3c000000, v199
	v_rsq_f32_e32 v0, v0
	v_lshlrev_b32_e32 v1, 16, v144
	v_mul_f32_e32 v16, 0xbfb8aa3b, v1
	v_exp_f32_e32 v16, v16
	v_mul_f32_e32 v2, v2, v0
	v_mul_f32_e32 v2, v113, v2
	v_add_f32_e32 v16, 1.0, v16
	v_rcp_f32_e32 v16, v16
	s_nop 0
	v_mul_f32_e32 v1, v16, v1
	v_mul_f32_e32 v1, v2, v1
	v_cvt_pk_bf16_f32 v1, v1, s0
	ds_write_b16 v138, v1 offset:8704
	v_mul_f32_e32 v2, v18, v0
	v_mul_f32_e32 v2, v130, v2
	v_lshlrev_b32_e32 v1, 16, v145
	v_mul_f32_e32 v16, 0xbfb8aa3b, v1
	v_exp_f32_e32 v16, v16
	s_nop 0
	v_add_f32_e32 v16, 1.0, v16
	v_rcp_f32_e32 v16, v16
	s_nop 0
	v_mul_f32_e32 v1, v16, v1
	v_mul_f32_e32 v1, v2, v1
	v_cvt_pk_bf16_f32 v1, v1, s0
	ds_write_b16 v138, v1 offset:8768
	v_mul_f32_e32 v2, v50, v0
	v_mul_f32_e32 v2, v131, v2
	v_mul_f32_e32 v0, v34, v0
	v_mul_f32_e32 v0, v132, v0
	v_lshlrev_b32_e32 v1, 16, v146
	v_mul_f32_e32 v16, 0xbfb8aa3b, v1
	v_exp_f32_e32 v16, v16
	s_nop 0
	v_add_f32_e32 v16, 1.0, v16
	v_rcp_f32_e32 v16, v16
	s_nop 0
	v_mul_f32_e32 v1, v16, v1
	v_mul_f32_e32 v1, v2, v1
	v_cvt_pk_bf16_f32 v1, v1, s0
	ds_write_b16 v138, v1 offset:8832
	v_lshlrev_b32_e32 v1, 16, v147
	v_mul_f32_e32 v2, 0xbfb8aa3b, v1
	v_exp_f32_e32 v2, v2
	s_nop 0
	v_add_f32_e32 v2, 1.0, v2
	v_rcp_f32_e32 v2, v2
	s_nop 0
	v_mul_f32_e32 v1, v2, v1
	v_mul_f32_e32 v0, v0, v1
	v_cvt_pk_bf16_f32 v0, v0, s0
	ds_write_b16 v138, v0 offset:8896
	v_mul_f32_e32 v0, v19, v19
	v_mul_f32_e32 v1, v35, v35
	v_fmac_f32_e32 v0, v3, v3
	v_fmac_f32_e32 v1, v51, v51
	v_add_f32_e32 v0, v0, v1
	ds_read_u16 v144, v138 offset:768
	ds_read_u16 v145, v138 offset:832
	ds_read_u16 v146, v138 offset:896
	ds_read_u16 v147, v138 offset:960
	s_nop 1
	v_add_f32_dpp v0, v0, v0 quad_perm:[1,0,3,2] row_mask:0xf bank_mask:0xf
	s_nop 1
	v_add_f32_dpp v0, v0, v0 quad_perm:[2,3,0,1] row_mask:0xf bank_mask:0xf
	s_nop 1
	v_add_f32_dpp v0, v0, v0 row_half_mirror row_mask:0xf bank_mask:0xf
	s_nop 1
	v_add_f32_dpp v0, v0, v0 row_mirror row_mask:0xf bank_mask:0xf
	s_waitcnt lgkmcnt(0)
	ds_bpermute_b32 v1, v137, v0
	s_waitcnt lgkmcnt(0)
	v_add_f32_e32 v0, v0, v1
	v_fmamk_f32 v0, v0, 0x3c000000, v199
	v_rsq_f32_e32 v0, v0
	v_lshlrev_b32_e32 v1, 16, v144
	v_mul_f32_e32 v2, v3, v0
	v_mul_f32_e32 v3, 0xbfb8aa3b, v1
	v_exp_f32_e32 v3, v3
	v_mul_f32_e32 v2, v113, v2
	v_add_f32_e32 v3, 1.0, v3
	v_rcp_f32_e32 v3, v3
	s_nop 0
	v_mul_f32_e32 v1, v3, v1
	v_mul_f32_e32 v1, v2, v1
	v_cvt_pk_bf16_f32 v1, v1, s0
	ds_write_b16 v138, v1 offset:8960
	v_mul_f32_e32 v2, v19, v0
	v_mul_f32_e32 v2, v130, v2
	v_lshlrev_b32_e32 v1, 16, v145
	v_mul_f32_e32 v3, 0xbfb8aa3b, v1
	v_exp_f32_e32 v3, v3
	s_nop 0
	v_add_f32_e32 v3, 1.0, v3
	v_rcp_f32_e32 v3, v3
	s_nop 0
	v_mul_f32_e32 v1, v3, v1
	v_mul_f32_e32 v1, v2, v1
	v_cvt_pk_bf16_f32 v1, v1, s0
	ds_write_b16 v138, v1 offset:9024
	v_mul_f32_e32 v2, v51, v0
	v_mul_f32_e32 v2, v131, v2
	v_mul_f32_e32 v0, v35, v0
	v_mul_f32_e32 v0, v132, v0
	v_lshlrev_b32_e32 v1, 16, v146
	v_mul_f32_e32 v3, 0xbfb8aa3b, v1
	v_exp_f32_e32 v3, v3
	s_nop 0
	v_add_f32_e32 v3, 1.0, v3
	v_rcp_f32_e32 v3, v3
	s_nop 0
	v_mul_f32_e32 v1, v3, v1
	v_mul_f32_e32 v1, v2, v1
	v_cvt_pk_bf16_f32 v1, v1, s0
	ds_write_b16 v138, v1 offset:9088
	v_lshlrev_b32_e32 v1, 16, v147
	v_mul_f32_e32 v2, 0xbfb8aa3b, v1
	v_exp_f32_e32 v2, v2
	s_nop 0
	v_add_f32_e32 v2, 1.0, v2
	v_rcp_f32_e32 v2, v2
	s_nop 0
	v_mul_f32_e32 v1, v2, v1
	v_mul_f32_e32 v0, v0, v1
	v_cvt_pk_bf16_f32 v0, v0, s0
	ds_write_b16 v138, v0 offset:9152
	v_mul_f32_e32 v0, v20, v20
	v_mul_f32_e32 v1, v36, v36
	v_fmac_f32_e32 v0, v4, v4
	v_fmac_f32_e32 v1, v52, v52
	v_add_f32_e32 v0, v0, v1
	ds_read_u16 v144, v138 offset:2048
	ds_read_u16 v145, v138 offset:2112
	ds_read_u16 v146, v138 offset:2176
	ds_read_u16 v147, v138 offset:2240
	s_nop 1
	v_add_f32_dpp v0, v0, v0 quad_perm:[1,0,3,2] row_mask:0xf bank_mask:0xf
	s_nop 1
	v_add_f32_dpp v0, v0, v0 quad_perm:[2,3,0,1] row_mask:0xf bank_mask:0xf
	s_nop 1
	v_add_f32_dpp v0, v0, v0 row_half_mirror row_mask:0xf bank_mask:0xf
	s_nop 1
	v_add_f32_dpp v0, v0, v0 row_mirror row_mask:0xf bank_mask:0xf
	s_waitcnt lgkmcnt(0)
; __device__ __forceinline__ int crow(int r, int hi) { return (r & 3) + 8 * (r >> 2) + 4 * hi; }
; __device__ __forceinline__ float bf2f(unsigned short v) { return __uint_as_float((unsigned)v << 16); }
; __device__ __forceinline__ unsigned f2bf(float f) { return pk2(f, 0.f) & 0xffffu; }
; __device__ __forceinline__ int crow(int r, int hi) { return (r & 3) + 8 * (r >> 2) + 4 * hi; }
; __device__ __forceinline__ void gla_pass_c(LAS unsigned char* ldsl, const bf16_t* __restrict__ proj, const float* __restrict__ Btab, const float* __restrict__ Gst, const float* __restrict__ gout, bf16_t* __restrict__ mixed) {
;     ...
;         for (int i = 0; i < 16; ++i) { const int tr = crow(i, hh);
;             const float tot = half_sum32((o[0][i] * o[0][i] + o[1][i] * o[1][i]) + (o[2][i] * o[2][i] + o[3][i] * o[3][i]));
;             const float rr = __builtin_amdgcn_rsqf(tot * (1.0f / 128.0f) + EPS);
; #pragma unroll
;             for (int dvb = 0; dvb < 4; ++dvb) { const float g = bf2f(Lh[tr * 128 + 32 * dvb + r]);
;                 const float val = o[dvb][i] * rr * gn[dvb] * (g * __builtin_amdgcn_rcpf(1.0f + __expf(-g)));
;                 Lh[(32 + tr) * 128 + 32 * dvb + r] = (bf16_t)f2bf(val); } }
	ds_bpermute_b32 v1, v137, v0
	s_waitcnt lgkmcnt(0)
	v_add_f32_e32 v0, v0, v1
	v_fmamk_f32 v0, v0, 0x3c000000, v199
	v_rsq_f32_e32 v0, v0
	v_lshlrev_b32_e32 v1, 16, v144
	v_mul_f32_e32 v3, 0xbfb8aa3b, v1
	v_exp_f32_e32 v3, v3
	v_mul_f32_e32 v2, v4, v0
	v_mul_f32_e32 v2, v113, v2
	v_add_f32_e32 v3, 1.0, v3
	v_rcp_f32_e32 v3, v3
	s_nop 0
	v_mul_f32_e32 v1, v3, v1
	v_mul_f32_e32 v1, v2, v1
	v_cvt_pk_bf16_f32 v1, v1, s0
	ds_write_b16 v138, v1 offset:10240
	v_mul_f32_e32 v2, v20, v0
	v_mul_f32_e32 v2, v130, v2
	v_lshlrev_b32_e32 v1, 16, v145
	v_mul_f32_e32 v3, 0xbfb8aa3b, v1
	v_exp_f32_e32 v3, v3
	s_nop 0
	v_add_f32_e32 v3, 1.0, v3
	v_rcp_f32_e32 v3, v3
	s_nop 0
	v_mul_f32_e32 v1, v3, v1
	v_mul_f32_e32 v1, v2, v1
	v_cvt_pk_bf16_f32 v1, v1, s0
	ds_write_b16 v138, v1 offset:10304
	v_mul_f32_e32 v2, v52, v0
	v_mul_f32_e32 v2, v131, v2
	v_mul_f32_e32 v0, v36, v0
	v_mul_f32_e32 v0, v132, v0
	v_lshlrev_b32_e32 v1, 16, v146
	v_mul_f32_e32 v3, 0xbfb8aa3b, v1
	v_exp_f32_e32 v3, v3
	s_nop 0
	v_add_f32_e32 v3, 1.0, v3
	v_rcp_f32_e32 v3, v3
	s_nop 0
	v_mul_f32_e32 v1, v3, v1
	v_mul_f32_e32 v1, v2, v1
	v_cvt_pk_bf16_f32 v1, v1, s0
	ds_write_b16 v138, v1 offset:10368
	v_lshlrev_b32_e32 v1, 16, v147
	v_mul_f32_e32 v2, 0xbfb8aa3b, v1
	v_exp_f32_e32 v2, v2
	s_nop 0
	v_add_f32_e32 v2, 1.0, v2
	v_rcp_f32_e32 v2, v2
	s_nop 0
	v_mul_f32_e32 v1, v2, v1
	v_mul_f32_e32 v0, v0, v1
	v_cvt_pk_bf16_f32 v0, v0, s0
	ds_write_b16 v138, v0 offset:10432
	v_mul_f32_e32 v0, v21, v21
	v_mul_f32_e32 v1, v37, v37
	v_fmac_f32_e32 v0, v5, v5
	v_fmac_f32_e32 v1, v53, v53
	v_add_f32_e32 v0, v0, v1
	ds_read_u16 v144, v138 offset:2304
	ds_read_u16 v145, v138 offset:2368
	ds_read_u16 v146, v138 offset:2432
	ds_read_u16 v147, v138 offset:2496
	s_nop 1
	v_add_f32_dpp v0, v0, v0 quad_perm:[1,0,3,2] row_mask:0xf bank_mask:0xf
	s_nop 1
	v_add_f32_dpp v0, v0, v0 quad_perm:[2,3,0,1] row_mask:0xf bank_mask:0xf
	s_nop 1
	v_add_f32_dpp v0, v0, v0 row_half_mirror row_mask:0xf bank_mask:0xf
	s_nop 1
	v_add_f32_dpp v0, v0, v0 row_mirror row_mask:0xf bank_mask:0xf
	s_waitcnt lgkmcnt(0)
	ds_bpermute_b32 v1, v137, v0
	s_waitcnt lgkmcnt(0)
	v_add_f32_e32 v0, v0, v1
	v_fmamk_f32 v0, v0, 0x3c000000, v199
	v_rsq_f32_e32 v0, v0
	v_lshlrev_b32_e32 v1, 16, v144
	v_mul_f32_e32 v3, 0xbfb8aa3b, v1
	v_exp_f32_e32 v3, v3
	v_mul_f32_e32 v2, v5, v0
	v_mul_f32_e32 v2, v113, v2
	v_add_f32_e32 v3, 1.0, v3
	v_rcp_f32_e32 v3, v3
	s_nop 0
	v_mul_f32_e32 v1, v3, v1
	v_mul_f32_e32 v1, v2, v1
	v_cvt_pk_bf16_f32 v1, v1, s0
	ds_write_b16 v138, v1 offset:10496
	v_mul_f32_e32 v2, v21, v0
	v_mul_f32_e32 v2, v130, v2
	v_lshlrev_b32_e32 v1, 16, v145
	v_mul_f32_e32 v3, 0xbfb8aa3b, v1
	v_exp_f32_e32 v3, v3
	s_nop 0
	v_add_f32_e32 v3, 1.0, v3
	v_rcp_f32_e32 v3, v3
	s_nop 0
	v_mul_f32_e32 v1, v3, v1
	v_mul_f32_e32 v1, v2, v1
	v_cvt_pk_bf16_f32 v1, v1, s0
	ds_write_b16 v138, v1 offset:10560
	v_mul_f32_e32 v2, v53, v0
	v_mul_f32_e32 v2, v131, v2
	v_mul_f32_e32 v0, v37, v0
	v_mul_f32_e32 v0, v132, v0
	v_lshlrev_b32_e32 v1, 16, v146
	v_mul_f32_e32 v3, 0xbfb8aa3b, v1
	v_exp_f32_e32 v3, v3
	s_nop 0
	v_add_f32_e32 v3, 1.0, v3
	v_rcp_f32_e32 v3, v3
	s_nop 0
	v_mul_f32_e32 v1, v3, v1
	v_mul_f32_e32 v1, v2, v1
	v_cvt_pk_bf16_f32 v1, v1, s0
	ds_write_b16 v138, v1 offset:10624
	v_lshlrev_b32_e32 v1, 16, v147
	v_mul_f32_e32 v2, 0xbfb8aa3b, v1
	v_exp_f32_e32 v2, v2
	s_nop 0
	v_add_f32_e32 v2, 1.0, v2
	v_rcp_f32_e32 v2, v2
	s_nop 0
	v_mul_f32_e32 v1, v2, v1
	v_mul_f32_e32 v0, v0, v1
	v_cvt_pk_bf16_f32 v0, v0, s0
	ds_write_b16 v138, v0 offset:10688
	v_mul_f32_e32 v0, v22, v22
	v_mul_f32_e32 v1, v38, v38
	v_fmac_f32_e32 v0, v6, v6
	v_fmac_f32_e32 v1, v54, v54
	v_add_f32_e32 v0, v0, v1
	ds_read_u16 v144, v138 offset:2560
	ds_read_u16 v145, v138 offset:2624
	ds_read_u16 v146, v138 offset:2688
	ds_read_u16 v147, v138 offset:2752
	s_nop 1
	v_add_f32_dpp v0, v0, v0 quad_perm:[1,0,3,2] row_mask:0xf bank_mask:0xf
	s_nop 1
	v_add_f32_dpp v0, v0, v0 quad_perm:[2,3,0,1] row_mask:0xf bank_mask:0xf
	s_nop 1
	v_add_f32_dpp v0, v0, v0 row_half_mirror row_mask:0xf bank_mask:0xf
	s_nop 1
	v_add_f32_dpp v0, v0, v0 row_mirror row_mask:0xf bank_mask:0xf
	s_waitcnt lgkmcnt(0)
	ds_bpermute_b32 v1, v137, v0
	s_waitcnt lgkmcnt(0)
	v_add_f32_e32 v0, v0, v1
	v_fmamk_f32 v0, v0, 0x3c000000, v199
	v_rsq_f32_e32 v0, v0
	v_lshlrev_b32_e32 v1, 16, v144
	v_mul_f32_e32 v3, 0xbfb8aa3b, v1
	v_exp_f32_e32 v3, v3
	v_mul_f32_e32 v2, v6, v0
	v_mul_f32_e32 v2, v113, v2
	v_add_f32_e32 v3, 1.0, v3
	v_rcp_f32_e32 v3, v3
	s_nop 0
	v_mul_f32_e32 v1, v3, v1
	v_mul_f32_e32 v1, v2, v1
	v_cvt_pk_bf16_f32 v1, v1, s0
	ds_write_b16 v138, v1 offset:10752
	v_mul_f32_e32 v2, v22, v0
	v_mul_f32_e32 v2, v130, v2
	v_lshlrev_b32_e32 v1, 16, v145
	v_mul_f32_e32 v3, 0xbfb8aa3b, v1
	v_exp_f32_e32 v3, v3
	s_nop 0
	v_add_f32_e32 v3, 1.0, v3
	v_rcp_f32_e32 v3, v3
	s_nop 0
	v_mul_f32_e32 v1, v3, v1
	v_mul_f32_e32 v1, v2, v1
	v_cvt_pk_bf16_f32 v1, v1, s0
	ds_write_b16 v138, v1 offset:10816
	v_mul_f32_e32 v2, v54, v0
	v_mul_f32_e32 v2, v131, v2
	v_mul_f32_e32 v0, v38, v0
	v_mul_f32_e32 v0, v132, v0
	v_lshlrev_b32_e32 v1, 16, v146
	v_mul_f32_e32 v3, 0xbfb8aa3b, v1
	v_exp_f32_e32 v3, v3
	s_nop 0
	v_add_f32_e32 v3, 1.0, v3
	v_rcp_f32_e32 v3, v3
	s_nop 0
	v_mul_f32_e32 v1, v3, v1
	v_mul_f32_e32 v1, v2, v1
	v_cvt_pk_bf16_f32 v1, v1, s0
	ds_write_b16 v138, v1 offset:10880
	v_lshlrev_b32_e32 v1, 16, v147
	v_mul_f32_e32 v2, 0xbfb8aa3b, v1
	v_exp_f32_e32 v2, v2
	s_nop 0
	v_add_f32_e32 v2, 1.0, v2
	v_rcp_f32_e32 v2, v2
	s_nop 0
	v_mul_f32_e32 v1, v2, v1
	v_mul_f32_e32 v0, v0, v1
	v_cvt_pk_bf16_f32 v0, v0, s0
	ds_write_b16 v138, v0 offset:10944
	v_mul_f32_e32 v0, v23, v23
	v_mul_f32_e32 v1, v39, v39
	v_fmac_f32_e32 v0, v7, v7
	v_fmac_f32_e32 v1, v55, v55
	v_add_f32_e32 v0, v0, v1
	ds_read_u16 v144, v138 offset:2816
	ds_read_u16 v145, v138 offset:2880
	ds_read_u16 v146, v138 offset:2944
	ds_read_u16 v147, v138 offset:3008
	s_nop 1
	v_add_f32_dpp v0, v0, v0 quad_perm:[1,0,3,2] row_mask:0xf bank_mask:0xf
	s_nop 1
	v_add_f32_dpp v0, v0, v0 quad_perm:[2,3,0,1] row_mask:0xf bank_mask:0xf
	s_nop 1
	v_add_f32_dpp v0, v0, v0 row_half_mirror row_mask:0xf bank_mask:0xf
	s_nop 1
	v_add_f32_dpp v0, v0, v0 row_mirror row_mask:0xf bank_mask:0xf
	s_waitcnt lgkmcnt(0)
; __device__ __forceinline__ int crow(int r, int hi) { return (r & 3) + 8 * (r >> 2) + 4 * hi; }
; __device__ __forceinline__ float bf2f(unsigned short v) { return __uint_as_float((unsigned)v << 16); }
; __device__ __forceinline__ unsigned f2bf(float f) { return pk2(f, 0.f) & 0xffffu; }
; __device__ __forceinline__ int crow(int r, int hi) { return (r & 3) + 8 * (r >> 2) + 4 * hi; }
; __device__ __forceinline__ void gla_pass_c(LAS unsigned char* ldsl, const bf16_t* __restrict__ proj, const float* __restrict__ Btab, const float* __restrict__ Gst, const float* __restrict__ gout, bf16_t* __restrict__ mixed) {
;     ...
;         for (int i = 0; i < 16; ++i) { const int tr = crow(i, hh);
;             const float tot = half_sum32((o[0][i] * o[0][i] + o[1][i] * o[1][i]) + (o[2][i] * o[2][i] + o[3][i] * o[3][i]));
;             const float rr = __builtin_amdgcn_rsqf(tot * (1.0f / 128.0f) + EPS);
; #pragma unroll
;             for (int dvb = 0; dvb < 4; ++dvb) { const float g = bf2f(Lh[tr * 128 + 32 * dvb + r]);
;                 const float val = o[dvb][i] * rr * gn[dvb] * (g * __builtin_amdgcn_rcpf(1.0f + __expf(-g)));
;                 Lh[(32 + tr) * 128 + 32 * dvb + r] = (bf16_t)f2bf(val); } }
	ds_bpermute_b32 v1, v137, v0
	s_waitcnt lgkmcnt(0)
	v_add_f32_e32 v0, v0, v1
	v_fmamk_f32 v0, v0, 0x3c000000, v199
	v_rsq_f32_e32 v0, v0
	v_lshlrev_b32_e32 v1, 16, v144
	v_mul_f32_e32 v3, 0xbfb8aa3b, v1
	v_exp_f32_e32 v3, v3
	v_mul_f32_e32 v2, v7, v0
	v_mul_f32_e32 v2, v113, v2
	v_add_f32_e32 v3, 1.0, v3
	v_rcp_f32_e32 v3, v3
	s_nop 0
	v_mul_f32_e32 v1, v3, v1
	v_mul_f32_e32 v1, v2, v1
	v_cvt_pk_bf16_f32 v1, v1, s0
	ds_write_b16 v138, v1 offset:11008
	v_mul_f32_e32 v2, v23, v0
	v_mul_f32_e32 v2, v130, v2
	v_lshlrev_b32_e32 v1, 16, v145
	v_mul_f32_e32 v3, 0xbfb8aa3b, v1
	v_exp_f32_e32 v3, v3
	s_nop 0
	v_add_f32_e32 v3, 1.0, v3
	v_rcp_f32_e32 v3, v3
	s_nop 0
	v_mul_f32_e32 v1, v3, v1
	v_mul_f32_e32 v1, v2, v1
	v_cvt_pk_bf16_f32 v1, v1, s0
	ds_write_b16 v138, v1 offset:11072
	v_mul_f32_e32 v2, v55, v0
	v_mul_f32_e32 v2, v131, v2
	v_mul_f32_e32 v0, v39, v0
	v_mul_f32_e32 v0, v132, v0
	v_lshlrev_b32_e32 v1, 16, v146
	v_mul_f32_e32 v3, 0xbfb8aa3b, v1
	v_exp_f32_e32 v3, v3
	s_nop 0
	v_add_f32_e32 v3, 1.0, v3
	v_rcp_f32_e32 v3, v3
	s_nop 0
	v_mul_f32_e32 v1, v3, v1
	v_mul_f32_e32 v1, v2, v1
	v_cvt_pk_bf16_f32 v1, v1, s0
	ds_write_b16 v138, v1 offset:11136
	v_lshlrev_b32_e32 v1, 16, v147
	v_mul_f32_e32 v2, 0xbfb8aa3b, v1
	v_exp_f32_e32 v2, v2
	s_nop 0
	v_add_f32_e32 v2, 1.0, v2
	v_rcp_f32_e32 v2, v2
	s_nop 0
	v_mul_f32_e32 v1, v2, v1
	v_mul_f32_e32 v0, v0, v1
	v_cvt_pk_bf16_f32 v0, v0, s0
	ds_write_b16 v138, v0 offset:11200
	v_mul_f32_e32 v0, v24, v24
	v_mul_f32_e32 v1, v40, v40
	v_fmac_f32_e32 v0, v8, v8
	v_fmac_f32_e32 v1, v56, v56
	v_add_f32_e32 v0, v0, v1
	ds_read_u16 v144, v138 offset:4096
	ds_read_u16 v145, v138 offset:4160
	ds_read_u16 v146, v138 offset:4224
	ds_read_u16 v147, v138 offset:4288
	s_nop 1
	v_add_f32_dpp v0, v0, v0 quad_perm:[1,0,3,2] row_mask:0xf bank_mask:0xf
	s_nop 1
	v_add_f32_dpp v0, v0, v0 quad_perm:[2,3,0,1] row_mask:0xf bank_mask:0xf
	s_nop 1
	v_add_f32_dpp v0, v0, v0 row_half_mirror row_mask:0xf bank_mask:0xf
	s_nop 1
	v_add_f32_dpp v0, v0, v0 row_mirror row_mask:0xf bank_mask:0xf
	s_waitcnt lgkmcnt(0)
	ds_bpermute_b32 v1, v137, v0
	s_waitcnt lgkmcnt(0)
	v_add_f32_e32 v0, v0, v1
	v_fmamk_f32 v0, v0, 0x3c000000, v199
	v_rsq_f32_e32 v0, v0
	v_lshlrev_b32_e32 v1, 16, v144
	v_mul_f32_e32 v3, 0xbfb8aa3b, v1
	v_exp_f32_e32 v3, v3
	v_mul_f32_e32 v2, v8, v0
	v_mul_f32_e32 v2, v113, v2
	v_add_f32_e32 v3, 1.0, v3
	v_rcp_f32_e32 v3, v3
	s_nop 0
	v_mul_f32_e32 v1, v3, v1
	v_mul_f32_e32 v1, v2, v1
	v_cvt_pk_bf16_f32 v1, v1, s0
	ds_write_b16 v138, v1 offset:12288
	v_mul_f32_e32 v2, v24, v0
	v_mul_f32_e32 v2, v130, v2
	v_lshlrev_b32_e32 v1, 16, v145
	v_mul_f32_e32 v3, 0xbfb8aa3b, v1
	v_exp_f32_e32 v3, v3
	s_nop 0
	v_add_f32_e32 v3, 1.0, v3
	v_rcp_f32_e32 v3, v3
	s_nop 0
	v_mul_f32_e32 v1, v3, v1
	v_mul_f32_e32 v1, v2, v1
	v_cvt_pk_bf16_f32 v1, v1, s0
	ds_write_b16 v138, v1 offset:12352
	v_mul_f32_e32 v2, v56, v0
	v_mul_f32_e32 v2, v131, v2
	v_mul_f32_e32 v0, v40, v0
	v_mul_f32_e32 v0, v132, v0
	v_lshlrev_b32_e32 v1, 16, v146
	v_mul_f32_e32 v3, 0xbfb8aa3b, v1
	v_exp_f32_e32 v3, v3
	s_nop 0
	v_add_f32_e32 v3, 1.0, v3
	v_rcp_f32_e32 v3, v3
	s_nop 0
	v_mul_f32_e32 v1, v3, v1
	v_mul_f32_e32 v1, v2, v1
	v_cvt_pk_bf16_f32 v1, v1, s0
	ds_write_b16 v138, v1 offset:12416
	v_lshlrev_b32_e32 v1, 16, v147
	v_mul_f32_e32 v2, 0xbfb8aa3b, v1
	v_exp_f32_e32 v2, v2
	s_nop 0
	v_add_f32_e32 v2, 1.0, v2
	v_rcp_f32_e32 v2, v2
	s_nop 0
	v_mul_f32_e32 v1, v2, v1
	v_mul_f32_e32 v0, v0, v1
	v_cvt_pk_bf16_f32 v0, v0, s0
	ds_write_b16 v138, v0 offset:12480
	v_mul_f32_e32 v0, v25, v25
	v_mul_f32_e32 v1, v41, v41
	v_fmac_f32_e32 v0, v9, v9
	v_fmac_f32_e32 v1, v57, v57
	v_add_f32_e32 v0, v0, v1
	ds_read_u16 v144, v138 offset:4352
	ds_read_u16 v145, v138 offset:4416
	ds_read_u16 v146, v138 offset:4480
	ds_read_u16 v147, v138 offset:4544
	s_nop 1
	v_add_f32_dpp v0, v0, v0 quad_perm:[1,0,3,2] row_mask:0xf bank_mask:0xf
	s_nop 1
	v_add_f32_dpp v0, v0, v0 quad_perm:[2,3,0,1] row_mask:0xf bank_mask:0xf
	s_nop 1
	v_add_f32_dpp v0, v0, v0 row_half_mirror row_mask:0xf bank_mask:0xf
	s_nop 1
	v_add_f32_dpp v0, v0, v0 row_mirror row_mask:0xf bank_mask:0xf
	s_waitcnt lgkmcnt(0)
	ds_bpermute_b32 v1, v137, v0
	s_waitcnt lgkmcnt(0)
	v_add_f32_e32 v0, v0, v1
	v_fmamk_f32 v0, v0, 0x3c000000, v199
	v_rsq_f32_e32 v0, v0
	v_lshlrev_b32_e32 v1, 16, v144
	v_mul_f32_e32 v3, 0xbfb8aa3b, v1
	v_exp_f32_e32 v3, v3
	v_mul_f32_e32 v2, v9, v0
	v_mul_f32_e32 v2, v113, v2
	v_add_f32_e32 v3, 1.0, v3
	v_rcp_f32_e32 v3, v3
	s_nop 0
	v_mul_f32_e32 v1, v3, v1
	v_mul_f32_e32 v1, v2, v1
	v_cvt_pk_bf16_f32 v1, v1, s0
	ds_write_b16 v138, v1 offset:12544
	v_mul_f32_e32 v2, v25, v0
	v_mul_f32_e32 v2, v130, v2
	v_lshlrev_b32_e32 v1, 16, v145
	v_mul_f32_e32 v3, 0xbfb8aa3b, v1
	v_exp_f32_e32 v3, v3
	s_nop 0
	v_add_f32_e32 v3, 1.0, v3
	v_rcp_f32_e32 v3, v3
	s_nop 0
	v_mul_f32_e32 v1, v3, v1
	v_mul_f32_e32 v1, v2, v1
	v_cvt_pk_bf16_f32 v1, v1, s0
	ds_write_b16 v138, v1 offset:12608
	v_mul_f32_e32 v2, v57, v0
	v_mul_f32_e32 v2, v131, v2
	v_mul_f32_e32 v0, v41, v0
	v_mul_f32_e32 v0, v132, v0
	v_lshlrev_b32_e32 v1, 16, v146
	v_mul_f32_e32 v3, 0xbfb8aa3b, v1
	v_exp_f32_e32 v3, v3
	s_nop 0
	v_add_f32_e32 v3, 1.0, v3
	v_rcp_f32_e32 v3, v3
	s_nop 0
	v_mul_f32_e32 v1, v3, v1
	v_mul_f32_e32 v1, v2, v1
	v_cvt_pk_bf16_f32 v1, v1, s0
	ds_write_b16 v138, v1 offset:12672
	v_lshlrev_b32_e32 v1, 16, v147
	v_mul_f32_e32 v2, 0xbfb8aa3b, v1
	v_exp_f32_e32 v2, v2
	s_nop 0
	v_add_f32_e32 v2, 1.0, v2
	v_rcp_f32_e32 v2, v2
	s_nop 0
	v_mul_f32_e32 v1, v2, v1
	v_mul_f32_e32 v0, v0, v1
	v_cvt_pk_bf16_f32 v0, v0, s0
	ds_write_b16 v138, v0 offset:12736
	v_mul_f32_e32 v0, v26, v26
	v_mul_f32_e32 v1, v42, v42
	v_fmac_f32_e32 v0, v10, v10
	v_fmac_f32_e32 v1, v58, v58
	v_add_f32_e32 v0, v0, v1
	ds_read_u16 v144, v138 offset:4608
	ds_read_u16 v145, v138 offset:4672
	ds_read_u16 v146, v138 offset:4736
	ds_read_u16 v147, v138 offset:4800
	s_nop 1
	v_add_f32_dpp v0, v0, v0 quad_perm:[1,0,3,2] row_mask:0xf bank_mask:0xf
	s_nop 1
	v_add_f32_dpp v0, v0, v0 quad_perm:[2,3,0,1] row_mask:0xf bank_mask:0xf
	s_nop 1
	v_add_f32_dpp v0, v0, v0 row_half_mirror row_mask:0xf bank_mask:0xf
	s_nop 1
	v_add_f32_dpp v0, v0, v0 row_mirror row_mask:0xf bank_mask:0xf
	s_waitcnt lgkmcnt(0)
; __device__ __forceinline__ int crow(int r, int hi) { return (r & 3) + 8 * (r >> 2) + 4 * hi; }
; __device__ __forceinline__ float bf2f(unsigned short v) { return __uint_as_float((unsigned)v << 16); }
; __device__ __forceinline__ unsigned f2bf(float f) { return pk2(f, 0.f) & 0xffffu; }
; __device__ __forceinline__ int crow(int r, int hi) { return (r & 3) + 8 * (r >> 2) + 4 * hi; }
; __device__ __forceinline__ void gla_pass_c(LAS unsigned char* ldsl, const bf16_t* __restrict__ proj, const float* __restrict__ Btab, const float* __restrict__ Gst, const float* __restrict__ gout, bf16_t* __restrict__ mixed) {
;     ...
;         for (int i = 0; i < 16; ++i) { const int tr = crow(i, hh);
;             const float tot = half_sum32((o[0][i] * o[0][i] + o[1][i] * o[1][i]) + (o[2][i] * o[2][i] + o[3][i] * o[3][i]));
;             const float rr = __builtin_amdgcn_rsqf(tot * (1.0f / 128.0f) + EPS);
; #pragma unroll
;             for (int dvb = 0; dvb < 4; ++dvb) { const float g = bf2f(Lh[tr * 128 + 32 * dvb + r]);
;                 const float val = o[dvb][i] * rr * gn[dvb] * (g * __builtin_amdgcn_rcpf(1.0f + __expf(-g)));
;                 Lh[(32 + tr) * 128 + 32 * dvb + r] = (bf16_t)f2bf(val); } }
	ds_bpermute_b32 v1, v137, v0
	s_waitcnt lgkmcnt(0)
	v_add_f32_e32 v0, v0, v1
	v_fmamk_f32 v0, v0, 0x3c000000, v199
	v_rsq_f32_e32 v0, v0
	v_lshlrev_b32_e32 v1, 16, v144
	v_mul_f32_e32 v3, 0xbfb8aa3b, v1
	v_exp_f32_e32 v3, v3
	v_mul_f32_e32 v2, v10, v0
	v_mul_f32_e32 v2, v113, v2
	v_add_f32_e32 v3, 1.0, v3
	v_rcp_f32_e32 v3, v3
	s_nop 0
	v_mul_f32_e32 v1, v3, v1
	v_mul_f32_e32 v1, v2, v1
	v_cvt_pk_bf16_f32 v1, v1, s0
	ds_write_b16 v138, v1 offset:12800
	v_mul_f32_e32 v2, v26, v0
	v_mul_f32_e32 v2, v130, v2
	v_lshlrev_b32_e32 v1, 16, v145
	v_mul_f32_e32 v3, 0xbfb8aa3b, v1
	v_exp_f32_e32 v3, v3
	s_nop 0
	v_add_f32_e32 v3, 1.0, v3
	v_rcp_f32_e32 v3, v3
	s_nop 0
	v_mul_f32_e32 v1, v3, v1
	v_mul_f32_e32 v1, v2, v1
	v_cvt_pk_bf16_f32 v1, v1, s0
	ds_write_b16 v138, v1 offset:12864
	v_mul_f32_e32 v2, v58, v0
	v_mul_f32_e32 v2, v131, v2
	v_mul_f32_e32 v0, v42, v0
	v_mul_f32_e32 v0, v132, v0
	v_lshlrev_b32_e32 v1, 16, v146
	v_mul_f32_e32 v3, 0xbfb8aa3b, v1
	v_exp_f32_e32 v3, v3
	s_nop 0
	v_add_f32_e32 v3, 1.0, v3
	v_rcp_f32_e32 v3, v3
	s_nop 0
	v_mul_f32_e32 v1, v3, v1
	v_mul_f32_e32 v1, v2, v1
	v_cvt_pk_bf16_f32 v1, v1, s0
	ds_write_b16 v138, v1 offset:12928
	v_lshlrev_b32_e32 v1, 16, v147
	v_mul_f32_e32 v2, 0xbfb8aa3b, v1
	v_exp_f32_e32 v2, v2
	s_nop 0
	v_add_f32_e32 v2, 1.0, v2
	v_rcp_f32_e32 v2, v2
	s_nop 0
	v_mul_f32_e32 v1, v2, v1
	v_mul_f32_e32 v0, v0, v1
	v_cvt_pk_bf16_f32 v0, v0, s0
	ds_write_b16 v138, v0 offset:12992
	v_mul_f32_e32 v0, v27, v27
	v_mul_f32_e32 v1, v43, v43
	v_fmac_f32_e32 v0, v11, v11
	v_fmac_f32_e32 v1, v59, v59
	v_add_f32_e32 v0, v0, v1
	ds_read_u16 v144, v138 offset:4864
	ds_read_u16 v145, v138 offset:4928
	ds_read_u16 v146, v138 offset:4992
	ds_read_u16 v147, v138 offset:5056
	s_nop 1
	v_add_f32_dpp v0, v0, v0 quad_perm:[1,0,3,2] row_mask:0xf bank_mask:0xf
	s_nop 1
	v_add_f32_dpp v0, v0, v0 quad_perm:[2,3,0,1] row_mask:0xf bank_mask:0xf
	s_nop 1
	v_add_f32_dpp v0, v0, v0 row_half_mirror row_mask:0xf bank_mask:0xf
	s_nop 1
	v_add_f32_dpp v0, v0, v0 row_mirror row_mask:0xf bank_mask:0xf
	s_waitcnt lgkmcnt(0)
	ds_bpermute_b32 v1, v137, v0
	s_waitcnt lgkmcnt(0)
	v_add_f32_e32 v0, v0, v1
	v_fmamk_f32 v0, v0, 0x3c000000, v199
	v_rsq_f32_e32 v0, v0
	v_lshlrev_b32_e32 v1, 16, v144
	v_mul_f32_e32 v3, 0xbfb8aa3b, v1
	v_exp_f32_e32 v3, v3
	v_mul_f32_e32 v2, v11, v0
	v_mul_f32_e32 v2, v113, v2
	v_add_f32_e32 v3, 1.0, v3
	v_rcp_f32_e32 v3, v3
	s_nop 0
	v_mul_f32_e32 v1, v3, v1
	v_mul_f32_e32 v1, v2, v1
	v_cvt_pk_bf16_f32 v1, v1, s0
	ds_write_b16 v138, v1 offset:13056
	v_mul_f32_e32 v2, v27, v0
	v_mul_f32_e32 v2, v130, v2
	v_lshlrev_b32_e32 v1, 16, v145
	v_mul_f32_e32 v3, 0xbfb8aa3b, v1
	v_exp_f32_e32 v3, v3
	s_nop 0
	v_add_f32_e32 v3, 1.0, v3
	v_rcp_f32_e32 v3, v3
	s_nop 0
	v_mul_f32_e32 v1, v3, v1
	v_mul_f32_e32 v1, v2, v1
	v_cvt_pk_bf16_f32 v1, v1, s0
	ds_write_b16 v138, v1 offset:13120
	v_mul_f32_e32 v2, v59, v0
	v_mul_f32_e32 v2, v131, v2
	v_mul_f32_e32 v0, v43, v0
	v_mul_f32_e32 v0, v132, v0
	v_lshlrev_b32_e32 v1, 16, v146
	v_mul_f32_e32 v3, 0xbfb8aa3b, v1
	v_exp_f32_e32 v3, v3
	s_nop 0
	v_add_f32_e32 v3, 1.0, v3
	v_rcp_f32_e32 v3, v3
	s_nop 0
	v_mul_f32_e32 v1, v3, v1
	v_mul_f32_e32 v1, v2, v1
	v_cvt_pk_bf16_f32 v1, v1, s0
	ds_write_b16 v138, v1 offset:13184
	v_lshlrev_b32_e32 v1, 16, v147
	v_mul_f32_e32 v2, 0xbfb8aa3b, v1
	v_exp_f32_e32 v2, v2
	s_nop 0
	v_add_f32_e32 v2, 1.0, v2
	v_rcp_f32_e32 v2, v2
	s_nop 0
	v_mul_f32_e32 v1, v2, v1
	v_mul_f32_e32 v0, v0, v1
	v_cvt_pk_bf16_f32 v0, v0, s0
	ds_write_b16 v138, v0 offset:13248
	v_mul_f32_e32 v0, v28, v28
	v_mul_f32_e32 v1, v44, v44
	v_fmac_f32_e32 v0, v12, v12
	v_fmac_f32_e32 v1, v60, v60
	v_add_f32_e32 v0, v0, v1
	ds_read_u16 v144, v138 offset:6144
	ds_read_u16 v145, v138 offset:6208
	ds_read_u16 v146, v138 offset:6272
	ds_read_u16 v147, v138 offset:6336
	s_nop 1
	v_add_f32_dpp v0, v0, v0 quad_perm:[1,0,3,2] row_mask:0xf bank_mask:0xf
	s_nop 1
	v_add_f32_dpp v0, v0, v0 quad_perm:[2,3,0,1] row_mask:0xf bank_mask:0xf
	s_nop 1
	v_add_f32_dpp v0, v0, v0 row_half_mirror row_mask:0xf bank_mask:0xf
	s_nop 1
	v_add_f32_dpp v0, v0, v0 row_mirror row_mask:0xf bank_mask:0xf
	s_waitcnt lgkmcnt(0)
	ds_bpermute_b32 v1, v137, v0
	s_waitcnt lgkmcnt(0)
	v_add_f32_e32 v0, v0, v1
	v_fmamk_f32 v0, v0, 0x3c000000, v199
	v_rsq_f32_e32 v0, v0
	v_lshlrev_b32_e32 v1, 16, v144
	v_mul_f32_e32 v3, 0xbfb8aa3b, v1
	v_exp_f32_e32 v3, v3
	v_mul_f32_e32 v2, v12, v0
	v_mul_f32_e32 v2, v113, v2
	v_add_f32_e32 v3, 1.0, v3
	v_rcp_f32_e32 v3, v3
	s_nop 0
	v_mul_f32_e32 v1, v3, v1
	v_mul_f32_e32 v1, v2, v1
	v_cvt_pk_bf16_f32 v1, v1, s0
	ds_write_b16 v138, v1 offset:14336
	v_mul_f32_e32 v2, v28, v0
	v_mul_f32_e32 v2, v130, v2
	v_lshlrev_b32_e32 v1, 16, v145
	v_mul_f32_e32 v3, 0xbfb8aa3b, v1
	v_exp_f32_e32 v3, v3
	s_nop 0
	v_add_f32_e32 v3, 1.0, v3
	v_rcp_f32_e32 v3, v3
	s_nop 0
	v_mul_f32_e32 v1, v3, v1
	v_mul_f32_e32 v1, v2, v1
	v_cvt_pk_bf16_f32 v1, v1, s0
	ds_write_b16 v138, v1 offset:14400
	v_mul_f32_e32 v2, v60, v0
	v_mul_f32_e32 v2, v131, v2
	v_mul_f32_e32 v0, v44, v0
	v_mul_f32_e32 v0, v132, v0
	v_lshlrev_b32_e32 v1, 16, v146
	v_mul_f32_e32 v3, 0xbfb8aa3b, v1
	v_exp_f32_e32 v3, v3
	s_nop 0
	v_add_f32_e32 v3, 1.0, v3
	v_rcp_f32_e32 v3, v3
	s_nop 0
	v_mul_f32_e32 v1, v3, v1
	v_mul_f32_e32 v1, v2, v1
	v_cvt_pk_bf16_f32 v1, v1, s0
	ds_write_b16 v138, v1 offset:14464
	v_lshlrev_b32_e32 v1, 16, v147
	v_mul_f32_e32 v2, 0xbfb8aa3b, v1
	v_exp_f32_e32 v2, v2
	s_nop 0
	v_add_f32_e32 v2, 1.0, v2
	v_rcp_f32_e32 v2, v2
	s_nop 0
	v_mul_f32_e32 v1, v2, v1
	v_mul_f32_e32 v0, v0, v1
	v_cvt_pk_bf16_f32 v0, v0, s0
	ds_write_b16 v138, v0 offset:14528
	v_mul_f32_e32 v0, v29, v29
	v_mul_f32_e32 v1, v45, v45
	v_fmac_f32_e32 v0, v13, v13
	v_fmac_f32_e32 v1, v61, v61
	v_add_f32_e32 v0, v0, v1
	ds_read_u16 v144, v138 offset:6400
	ds_read_u16 v145, v138 offset:6464
	ds_read_u16 v146, v138 offset:6528
	ds_read_u16 v147, v138 offset:6592
	s_nop 1
	v_add_f32_dpp v0, v0, v0 quad_perm:[1,0,3,2] row_mask:0xf bank_mask:0xf
	s_nop 1
	v_add_f32_dpp v0, v0, v0 quad_perm:[2,3,0,1] row_mask:0xf bank_mask:0xf
	s_nop 1
	v_add_f32_dpp v0, v0, v0 row_half_mirror row_mask:0xf bank_mask:0xf
	s_nop 1
	v_add_f32_dpp v0, v0, v0 row_mirror row_mask:0xf bank_mask:0xf
	s_waitcnt lgkmcnt(0)
; __device__ __forceinline__ int crow(int r, int hi) { return (r & 3) + 8 * (r >> 2) + 4 * hi; }
; __device__ __forceinline__ float bf2f(unsigned short v) { return __uint_as_float((unsigned)v << 16); }
; __device__ __forceinline__ unsigned f2bf(float f) { return pk2(f, 0.f) & 0xffffu; }
; __device__ __forceinline__ int crow(int r, int hi) { return (r & 3) + 8 * (r >> 2) + 4 * hi; }
; __device__ __forceinline__ void gla_pass_c(LAS unsigned char* ldsl, const bf16_t* __restrict__ proj, const float* __restrict__ Btab, const float* __restrict__ Gst, const float* __restrict__ gout, bf16_t* __restrict__ mixed) {
;     ...
;         for (int i = 0; i < 16; ++i) { const int tr = crow(i, hh);
;             const float tot = half_sum32((o[0][i] * o[0][i] + o[1][i] * o[1][i]) + (o[2][i] * o[2][i] + o[3][i] * o[3][i]));
;             const float rr = __builtin_amdgcn_rsqf(tot * (1.0f / 128.0f) + EPS);
; #pragma unroll
;             for (int dvb = 0; dvb < 4; ++dvb) { const float g = bf2f(Lh[tr * 128 + 32 * dvb + r]);
;                 const float val = o[dvb][i] * rr * gn[dvb] * (g * __builtin_amdgcn_rcpf(1.0f + __expf(-g)));
;                 Lh[(32 + tr) * 128 + 32 * dvb + r] = (bf16_t)f2bf(val); } }
	ds_bpermute_b32 v1, v137, v0
	s_waitcnt lgkmcnt(0)
	v_add_f32_e32 v0, v0, v1
	v_fmamk_f32 v0, v0, 0x3c000000, v199
	v_rsq_f32_e32 v0, v0
	v_lshlrev_b32_e32 v1, 16, v144
	v_mul_f32_e32 v3, 0xbfb8aa3b, v1
	v_exp_f32_e32 v3, v3
	v_mul_f32_e32 v2, v13, v0
	v_mul_f32_e32 v2, v113, v2
	v_add_f32_e32 v3, 1.0, v3
	v_rcp_f32_e32 v3, v3
	s_nop 0
	v_mul_f32_e32 v1, v3, v1
	v_mul_f32_e32 v1, v2, v1
	v_cvt_pk_bf16_f32 v1, v1, s0
	ds_write_b16 v138, v1 offset:14592
	v_mul_f32_e32 v2, v29, v0
	v_mul_f32_e32 v2, v130, v2
	v_lshlrev_b32_e32 v1, 16, v145
	v_mul_f32_e32 v3, 0xbfb8aa3b, v1
	v_exp_f32_e32 v3, v3
	s_nop 0
	v_add_f32_e32 v3, 1.0, v3
	v_rcp_f32_e32 v3, v3
	s_nop 0
	v_mul_f32_e32 v1, v3, v1
	v_mul_f32_e32 v1, v2, v1
	v_cvt_pk_bf16_f32 v1, v1, s0
	ds_write_b16 v138, v1 offset:14656
	v_mul_f32_e32 v2, v61, v0
	v_mul_f32_e32 v2, v131, v2
	v_mul_f32_e32 v0, v45, v0
	v_mul_f32_e32 v0, v132, v0
	v_lshlrev_b32_e32 v1, 16, v146
	v_mul_f32_e32 v3, 0xbfb8aa3b, v1
	v_exp_f32_e32 v3, v3
	s_nop 0
	v_add_f32_e32 v3, 1.0, v3
	v_rcp_f32_e32 v3, v3
	s_nop 0
	v_mul_f32_e32 v1, v3, v1
	v_mul_f32_e32 v1, v2, v1
	v_cvt_pk_bf16_f32 v1, v1, s0
	ds_write_b16 v138, v1 offset:14720
	v_lshlrev_b32_e32 v1, 16, v147
	v_mul_f32_e32 v2, 0xbfb8aa3b, v1
	v_exp_f32_e32 v2, v2
	s_nop 0
	v_add_f32_e32 v2, 1.0, v2
	v_rcp_f32_e32 v2, v2
	s_nop 0
	v_mul_f32_e32 v1, v2, v1
	v_mul_f32_e32 v0, v0, v1
	v_cvt_pk_bf16_f32 v0, v0, s0
	ds_write_b16 v138, v0 offset:14784
	v_mul_f32_e32 v0, v30, v30
	v_mul_f32_e32 v1, v46, v46
	v_fmac_f32_e32 v0, v14, v14
	v_fmac_f32_e32 v1, v62, v62
	v_add_f32_e32 v0, v0, v1
	ds_read_u16 v144, v138 offset:6656
	ds_read_u16 v145, v138 offset:6720
	ds_read_u16 v146, v138 offset:6784
	ds_read_u16 v147, v138 offset:6848
	s_nop 1
	v_add_f32_dpp v0, v0, v0 quad_perm:[1,0,3,2] row_mask:0xf bank_mask:0xf
	s_nop 1
	v_add_f32_dpp v0, v0, v0 quad_perm:[2,3,0,1] row_mask:0xf bank_mask:0xf
	s_nop 1
	v_add_f32_dpp v0, v0, v0 row_half_mirror row_mask:0xf bank_mask:0xf
	s_nop 1
	v_add_f32_dpp v0, v0, v0 row_mirror row_mask:0xf bank_mask:0xf
	s_waitcnt lgkmcnt(0)
	ds_bpermute_b32 v1, v137, v0
	s_waitcnt lgkmcnt(0)
	v_add_f32_e32 v0, v0, v1
	v_fmamk_f32 v0, v0, 0x3c000000, v199
	v_rsq_f32_e32 v0, v0
	v_lshlrev_b32_e32 v1, 16, v144
	v_mul_f32_e32 v3, 0xbfb8aa3b, v1
	v_exp_f32_e32 v3, v3
	v_mul_f32_e32 v2, v14, v0
	v_mul_f32_e32 v2, v113, v2
	v_add_f32_e32 v3, 1.0, v3
	v_rcp_f32_e32 v3, v3
	s_nop 0
	v_mul_f32_e32 v1, v3, v1
	v_mul_f32_e32 v1, v2, v1
	v_cvt_pk_bf16_f32 v1, v1, s0
	ds_write_b16 v138, v1 offset:14848
	v_mul_f32_e32 v2, v30, v0
	v_mul_f32_e32 v2, v130, v2
	v_lshlrev_b32_e32 v1, 16, v145
	v_mul_f32_e32 v3, 0xbfb8aa3b, v1
	v_exp_f32_e32 v3, v3
	s_nop 0
	v_add_f32_e32 v3, 1.0, v3
	v_rcp_f32_e32 v3, v3
	s_nop 0
	v_mul_f32_e32 v1, v3, v1
	v_mul_f32_e32 v1, v2, v1
	v_cvt_pk_bf16_f32 v1, v1, s0
	ds_write_b16 v138, v1 offset:14912
	v_mul_f32_e32 v2, v62, v0
	v_mul_f32_e32 v2, v131, v2
	v_mul_f32_e32 v0, v46, v0
	v_mul_f32_e32 v0, v132, v0
	v_lshlrev_b32_e32 v1, 16, v146
	v_mul_f32_e32 v3, 0xbfb8aa3b, v1
	v_exp_f32_e32 v3, v3
	s_nop 0
	v_add_f32_e32 v3, 1.0, v3
	v_rcp_f32_e32 v3, v3
	s_nop 0
	v_mul_f32_e32 v1, v3, v1
	v_mul_f32_e32 v1, v2, v1
	v_cvt_pk_bf16_f32 v1, v1, s0
	ds_write_b16 v138, v1 offset:14976
	v_lshlrev_b32_e32 v1, 16, v147
	v_mul_f32_e32 v2, 0xbfb8aa3b, v1
	v_exp_f32_e32 v2, v2
	s_nop 0
	v_add_f32_e32 v2, 1.0, v2
	v_rcp_f32_e32 v2, v2
	s_nop 0
	v_mul_f32_e32 v1, v2, v1
	v_mul_f32_e32 v0, v0, v1
	v_cvt_pk_bf16_f32 v0, v0, s0
	ds_write_b16 v138, v0 offset:15040
	v_mul_f32_e32 v0, v31, v31
	v_mul_f32_e32 v1, v47, v47
	v_fmac_f32_e32 v0, v15, v15
	v_fmac_f32_e32 v1, v63, v63
	v_add_f32_e32 v0, v0, v1
	ds_read_u16 v144, v138 offset:6912
	ds_read_u16 v145, v138 offset:6976
	ds_read_u16 v146, v138 offset:7040
	ds_read_u16 v147, v138 offset:7104
	s_nop 1
	v_add_f32_dpp v0, v0, v0 quad_perm:[1,0,3,2] row_mask:0xf bank_mask:0xf
	s_nop 1
	v_add_f32_dpp v0, v0, v0 quad_perm:[2,3,0,1] row_mask:0xf bank_mask:0xf
	s_nop 1
	v_add_f32_dpp v0, v0, v0 row_half_mirror row_mask:0xf bank_mask:0xf
	s_nop 1
	v_add_f32_dpp v0, v0, v0 row_mirror row_mask:0xf bank_mask:0xf
	s_waitcnt lgkmcnt(0)
; #define LAS __attribute__((address_space(3)))
; __device__ __forceinline__ int crow(int r, int hi) { return (r & 3) + 8 * (r >> 2) + 4 * hi; }
; __device__ __forceinline__ float bf2f(unsigned short v) { return __uint_as_float((unsigned)v << 16); }
; __device__ __forceinline__ unsigned f2bf(float f) { return pk2(f, 0.f) & 0xffffu; }
; __device__ __forceinline__ int crow(int r, int hi) { return (r & 3) + 8 * (r >> 2) + 4 * hi; }
; __device__ __forceinline__ void gla_pass_c(LAS unsigned char* ldsl, const bf16_t* __restrict__ proj, const float* __restrict__ Btab, const float* __restrict__ Gst, const float* __restrict__ gout, bf16_t* __restrict__ mixed) {
;     ...
;     for (int u = gw; u < 16 * 128 * 2; u += NGW) { const int item = u >> 1, tb = __builtin_amdgcn_readfirstlane((u ^ (u >> 11) ^ (u >> 3)) & 1);
;     ...
;         for (int i = 0; i < 16; ++i) { const int tr = crow(i, hh);
;             const float tot = half_sum32((o[0][i] * o[0][i] + o[1][i] * o[1][i]) + (o[2][i] * o[2][i] + o[3][i] * o[3][i]));
;             const float rr = __builtin_amdgcn_rsqf(tot * (1.0f / 128.0f) + EPS);
; #pragma unroll
;             for (int dvb = 0; dvb < 4; ++dvb) { const float g = bf2f(Lh[tr * 128 + 32 * dvb + r]);
;                 const float val = o[dvb][i] * rr * gn[dvb] * (g * __builtin_amdgcn_rcpf(1.0f + __expf(-g)));
;                 Lh[(32 + tr) * 128 + 32 * dvb + r] = (bf16_t)f2bf(val); } }
;         { bf16_t* mp = mixed + (row0 + 32 * tb + crw) * DM + h * 128 + ccl * 8;
; #pragma unroll
;           for (int i = 0; i < 8; ++i) *(u32x4*)(mp + (size_t)(4 * i) * DM) = *(const LAS u32x4*)(Lw + (32 + 4 * i + crw) * 256 + ccl * 16); }
	ds_bpermute_b32 v1, v137, v0
	s_waitcnt lgkmcnt(0)
	v_add_f32_e32 v0, v0, v1
	v_fmamk_f32 v0, v0, 0x3c000000, v199
	v_rsq_f32_e32 v0, v0
	v_lshlrev_b32_e32 v1, 16, v144
	v_mul_f32_e32 v3, 0xbfb8aa3b, v1
	v_exp_f32_e32 v3, v3
	v_mul_f32_e32 v2, v15, v0
	v_mul_f32_e32 v2, v113, v2
	v_add_f32_e32 v3, 1.0, v3
	v_rcp_f32_e32 v3, v3
	s_nop 0
	v_mul_f32_e32 v1, v3, v1
	v_mul_f32_e32 v1, v2, v1
	v_cvt_pk_bf16_f32 v1, v1, s0
	ds_write_b16 v138, v1 offset:15104
	v_mul_f32_e32 v2, v31, v0
	v_mul_f32_e32 v2, v130, v2
	v_lshlrev_b32_e32 v1, 16, v145
	v_mul_f32_e32 v3, 0xbfb8aa3b, v1
	v_exp_f32_e32 v3, v3
	s_nop 0
	v_add_f32_e32 v3, 1.0, v3
	v_rcp_f32_e32 v3, v3
	s_nop 0
	v_mul_f32_e32 v1, v3, v1
	v_mul_f32_e32 v1, v2, v1
	v_cvt_pk_bf16_f32 v1, v1, s0
	ds_write_b16 v138, v1 offset:15168
	v_mul_f32_e32 v2, v63, v0
	v_mul_f32_e32 v2, v131, v2
	v_mul_f32_e32 v0, v47, v0
	v_mul_f32_e32 v0, v132, v0
	v_lshlrev_b32_e32 v1, 16, v146
	v_mul_f32_e32 v3, 0xbfb8aa3b, v1
	v_exp_f32_e32 v3, v3
	s_nop 0
	v_add_f32_e32 v3, 1.0, v3
	v_rcp_f32_e32 v3, v3
	s_nop 0
	v_mul_f32_e32 v1, v3, v1
	v_mul_f32_e32 v1, v2, v1
	v_cvt_pk_bf16_f32 v1, v1, s0
	ds_write_b16 v138, v1 offset:15232
	v_lshlrev_b32_e32 v1, 16, v147
	v_mul_f32_e32 v2, 0xbfb8aa3b, v1
	v_exp_f32_e32 v2, v2
	s_nop 0
	v_add_f32_e32 v2, 1.0, v2
	v_rcp_f32_e32 v2, v2
	s_nop 0
	v_mul_f32_e32 v1, v2, v1
	v_mul_f32_e32 v0, v0, v1
	v_cvt_pk_bf16_f32 v0, v0, s0
	ds_write_b16 v138, v0 offset:15296
	v_lshlrev_b64 v[0:1], 11, v[122:123]
	v_lshl_add_u64 v[0:1], s[54:55], 0, v[0:1]
	v_lshl_add_u64 v[0:1], v[0:1], 0, v[160:161]
	v_lshl_add_u64 v[4:5], v[0:1], 0, v[120:121]
	ds_read_b128 v[8:11], v140 offset:8192
	ds_read_b128 v[12:15], v140 offset:9216
	ds_read_b128 v[16:19], v140 offset:10240
	ds_read_b128 v[20:23], v140 offset:11264
	ds_read_b128 v[24:27], v140 offset:12288
	ds_read_b128 v[28:31], v140 offset:13312
	ds_read_b128 v[32:35], v140 offset:14336
	ds_read_b128 v[36:39], v140 offset:15360
	v_add_co_u32_e32 v6, vcc, s2, v4
	s_movk_i32 s2, 0x6000
	s_nop 0
	v_addc_co_u32_e32 v7, vcc, 0, v5, vcc
	s_waitcnt lgkmcnt(7)
	global_store_dwordx4 v[4:5], v[8:11], off
	s_waitcnt lgkmcnt(6)
	global_store_dwordx4 v[6:7], v[12:15], off
	v_add_co_u32_e32 v6, vcc, s49, v4
	s_nop 1
	v_addc_co_u32_e32 v7, vcc, 0, v5, vcc
	s_waitcnt lgkmcnt(5)
	global_store_dwordx4 v[6:7], v[16:19], off
	v_add_co_u32_e32 v6, vcc, s2, v4
	s_mov_b32 s2, 0xa000
	s_nop 0
	v_addc_co_u32_e32 v7, vcc, 0, v5, vcc
	s_waitcnt lgkmcnt(4)
	global_store_dwordx4 v[6:7], v[20:23], off
	v_add_co_u32_e32 v6, vcc, s42, v4
	s_nop 1
	v_addc_co_u32_e32 v7, vcc, 0, v5, vcc
	s_waitcnt lgkmcnt(3)
	global_store_dwordx4 v[6:7], v[24:27], off
	v_add_co_u32_e32 v6, vcc, s2, v4
	s_movk_i32 s2, 0x7ff
	s_nop 0
	v_addc_co_u32_e32 v7, vcc, 0, v5, vcc
	s_waitcnt lgkmcnt(2)
	global_store_dwordx4 v[6:7], v[28:31], off
	v_add_co_u32_e32 v6, vcc, 0xc000, v4
	s_nop 1
	v_addc_co_u32_e32 v7, vcc, 0, v5, vcc
	s_waitcnt lgkmcnt(1)
	global_store_dwordx4 v[6:7], v[32:35], off
	v_add_co_u32_e32 v4, vcc, 0xe000, v4
	s_nop 1
	v_addc_co_u32_e32 v5, vcc, 0, v5, vcc
	s_waitcnt lgkmcnt(0)
	global_store_dwordx4 v[4:5], v[36:39], off
	v_cmp_lt_i32_e32 vcc, s2, v111
	s_or_b64 s[40:41], vcc, s[40:41]
	v_add_u32_e32 v0, 0x800, v111
	v_mov_b32_e32 v111, v0
	s_andn2_b64 exec, exec, s[40:41]
	s_cbranch_execz .LBB0_880
